# P6->P1 seam: the XCC leader issues its release add without first waiting for the cross-XCC generation add (same trim as the other seams)
# baseline (speedup 1.0000x reference)
; __device__ __forceinline__ unsigned xb_ld(unsigned* p)              { return __hip_atomic_load(p, __ATOMIC_RELAXED, __HIP_MEMORY_SCOPE_AGENT); }
; __device__ __forceinline__ unsigned xb_add(unsigned* p, unsigned v) { return __hip_atomic_fetch_add(p, v, __ATOMIC_RELAXED, __HIP_MEMORY_SCOPE_AGENT); }
; #define XB_SPIN(cond, bar) do { unsigned _sp = 0; while (cond) { __builtin_amdgcn_s_sleep(1); \
;     if ((++_sp & 255u) == 0u) { if (xb_ld(&(bar)[XB_TMO])) break; if (_sp > XB_SPIN_CAP) { atomicAdd(&(bar)[XB_TMO], 1u); break; } } } } while (0)
; __device__ __forceinline__ void xcd_barrier(const XcdBarrier& b) {
;     ...
;         const unsigned old = xb_add(&bar[XB_XSUB(b.x)], 1u);
;         const unsigned gen = old / nloc;
;         if (old + 1u == (gen + 1u) * nloc) {
;             __builtin_amdgcn_fence(__ATOMIC_RELEASE, "agent");
;             asm volatile("s_waitcnt vmcnt(0)" ::: "memory");
;             const unsigned og = xb_add(&bar[XB_TOP], 1u);
;             const unsigned tg = og / nx;
;             if (og + 1u == (tg + 1u) * nx) xb_add(&bar[XB_TOPGEN], 1u);
;             else XB_SPIN(xb_ld(&bar[XB_TOPGEN]) == tg, bar);
;             __builtin_amdgcn_fence(__ATOMIC_ACQUIRE, "agent");
;             xb_add(&bar[XB_XGEN(b.x)], 1u);
;             asm volatile("s_waitcnt vmcnt(0)" ::: "memory");
.LBB0_817:
	s_or_b64 exec, exec, s[38:39]
	s_mov_b64 s[38:39], exec
	v_mbcnt_lo_u32_b32 v0, s38, 0
	v_mbcnt_hi_u32_b32 v0, s39, v0
	v_cmp_eq_u32_e32 vcc, 0, v0
	s_nop 0
	s_and_saveexec_b64 s[40:41], vcc
	s_cbranch_execnz .LBB0_818
	s_getpc_b64 s[98:99]
